# static s_setprio 1 for waves 4-7 during the attention phase (7.4) on top of peeled first iteration + kinner_bj
# baseline (speedup 1.0000x reference)
.LBB0_845:
	s_ashr_i32 s1, s0, 31
	v_readlane_b32 s2, v254, 13
	s_xor_b32 s1, s1, s2
	s_abs_i32 s2, s0
	v_readlane_b32 s5, v254, 15
	s_mul_hi_u32 s5, s2, s5
	v_readlane_b32 s12, v254, 14
	s_mul_i32 s10, s5, s12
	s_sub_i32 s2, s2, s10
	s_add_i32 s10, s5, 1
	s_sub_i32 s11, s2, s12
	s_cmp_ge_u32 s2, s12
	s_cselect_b32 s5, s10, s5
	s_cselect_b32 s2, s11, s2
	s_add_i32 s10, s5, 1
	s_cmp_ge_u32 s2, s12
	s_cselect_b32 s2, s10, s5
	s_xor_b32 s2, s2, s1
	s_sub_i32 s35, s2, s1
	v_readlane_b32 s1, v253, 33
	s_mul_i32 s1, s35, s1
	s_sub_i32 s50, s0, s1
	v_readlane_b32 s0, v253, 19
	s_cmp_ge_i32 s50, s0
	s_barrier
	s_cbranch_scc1 .LBB0_938
	v_readlane_b32 s0, v253, 9
	s_nop 3
	s_cmp_lt_u32 s0, 4
	s_cbranch_scc1 .Latt_prio_skip
	s_setprio 1
.Latt_prio_skip:
	s_add_u32 s52, s14, 0x35800000
	s_addc_u32 s53, s15, 0
	s_lshl_b32 s0, s4, 1
	s_add_u32 s81, s52, s0
	s_addc_u32 s57, s53, 0
	s_add_u32 s79, s14, 0x4c800000
	s_addc_u32 s0, s15, 0
	s_add_u32 s1, s14, 0x100000
	s_addc_u32 s60, s15, 0
	v_readlane_b32 s2, v255, 2
	s_add_u32 s2, s14, s2
	s_addc_u32 s4, s15, 0
	s_add_u32 s96, s2, 0x3000000
	s_addc_u32 s97, s4, 0
	s_add_u32 s84, s2, 0x3800000
	s_addc_u32 s51, s4, 0
	s_add_u32 s68, s14, 0x2d800000
	v_readlane_b32 s26, v253, 25
	s_addc_u32 s69, s15, 0
	s_sub_i32 s2, s50, s26
	s_lshr_b32 s4, s2, 6
	s_lshl_b32 s4, s4, s85
	s_add_i32 s4, s4, s35
	s_lshl_b32 s5, s4, 4
	s_bfe_u32 s10, s2, 0x40002
	s_or_b32 s10, s5, s10
	s_ashr_i32 s11, s10, 31
	s_lshl_b64 s[16:17], s[10:11], 20
	s_add_u32 s5, s68, s16
	s_addc_u32 s11, s69, s17
	s_lshl_b32 s2, s2, 8
	s_and_b32 s2, s2, 0x300
	s_add_u32 s5, s5, s2
	s_addc_u32 s11, s11, 0
	s_add_u32 s24, s5, 0xc00
	s_addc_u32 s25, s11, 0
	s_ashr_i32 s5, s4, 31
	s_lshl_b64 s[4:5], s[4:5], 18
	s_add_u32 s11, s84, s4
	s_addc_u32 s12, s51, s5
	s_add_u32 s22, s11, s2
	s_addc_u32 s23, s12, 0
	s_add_u32 s4, s96, s4
	s_addc_u32 s5, s97, s5
	s_add_u32 s20, s4, s2
	v_readlane_b32 s4, v254, 55
	s_addc_u32 s21, s5, 0
	s_mul_hi_i32 s5, s4, s10
	s_mul_i32 s4, s4, s10
	s_lshl_b64 s[4:5], s[4:5], 1
	s_add_u32 s4, s81, s4
	s_addc_u32 s5, s57, s5
	s_add_u32 s18, s4, s2
	s_addc_u32 s19, s5, 0
	s_cmp_ge_i32 s50, s26
	s_cbranch_scc1 .LBB0_848
	v_mbcnt_lo_u32_b32 v0, -1, 0
	v_mbcnt_hi_u32_b32 v0, -1, v0
	s_abs_i32 s5, s50
	v_cmp_gt_i32_e32 vcc, 12, v0
	v_readlane_b32 s10, v254, 17
	s_mul_hi_u32 s10, s5, s10
	v_cndmask_b32_e32 v4, 11, v0, vcc
	v_ashrrev_i32_e32 v5, 31, v4
	v_lshl_add_u64 v[4:5], v[4:5], 2, s[8:9]
	global_load_dword v1, v[4:5], off
	v_readlane_b32 s16, v254, 16
	s_mul_i32 s11, s10, s16
	s_lshl_b32 s2, s50, 8
	s_sub_i32 s5, s5, s11
	s_and_b32 s2, s2, 0x700
	s_ashr_i32 s4, s50, 31
	s_add_i32 s11, s10, 1
	s_sub_i32 s12, s5, s16
	s_cmp_ge_u32 s5, s16
	s_cselect_b32 s10, s11, s10
	s_cselect_b32 s5, s12, s5
	s_add_i32 s11, s10, 1
	s_cmp_ge_u32 s5, s16
	s_cselect_b32 s5, s11, s10
	v_cmp_lt_i32_e64 s[40:41], 0, v0
	s_xor_b32 s5, s5, s4
	s_sub_i32 s5, s5, s4
	v_readlane_b32 s4, v254, 12
	s_lshl_b32 s4, s5, s4
	s_sub_i32 s4, s50, s4
	s_ashr_i32 s4, s4, 3
	s_lshl_b32 s4, s4, s85
	s_add_i32 s4, s4, s35
	s_movk_i32 s49, 0x1000
	s_movk_i32 s58, 0xc00
	s_waitcnt vmcnt(0)
	v_readlane_b32 s10, v1, 0
	s_nop 1
	v_cmp_eq_f32_e64 s[38:39], s10, v1
	v_cmp_gt_f32_e64 s[36:37], s10, v1
	s_and_b64 s[10:11], s[40:41], s[38:39]
	s_or_b64 s[10:11], s[36:37], s[10:11]
	v_cndmask_b32_e64 v2, 0, 1, s[10:11]
	v_readlane_b32 s10, v1, 1
	v_cmp_lt_i32_e64 s[40:41], 1, v0
	s_nop 0
	v_cmp_eq_f32_e64 s[38:39], s10, v1
	v_cmp_gt_f32_e64 s[36:37], s10, v1
	s_and_b64 s[10:11], s[40:41], s[38:39]
	s_or_b64 s[36:37], s[36:37], s[10:11]
	v_readlane_b32 s10, v1, 2
	v_addc_co_u32_e64 v2, s[36:37], 0, v2, s[36:37]
	s_nop 0
	v_cmp_eq_f32_e64 s[38:39], s10, v1
	v_cmp_lt_i32_e64 s[40:41], 2, v0
	v_cmp_gt_f32_e64 s[36:37], s10, v1
	s_and_b64 s[10:11], s[40:41], s[38:39]
	s_or_b64 s[10:11], s[36:37], s[10:11]
	v_cndmask_b32_e64 v4, 0, 1, s[10:11]
	v_readlane_b32 s10, v1, 3
	v_cmp_lt_i32_e64 s[40:41], 3, v0
	s_nop 0
	v_cmp_eq_f32_e64 s[38:39], s10, v1
	v_cmp_gt_f32_e64 s[36:37], s10, v1
	s_and_b64 s[10:11], s[40:41], s[38:39]
	s_or_b64 s[36:37], s[36:37], s[10:11]
	v_readlane_b32 s10, v1, 4
	v_addc_co_u32_e64 v2, s[36:37], v2, v4, s[36:37]
	s_nop 0
	v_cmp_eq_f32_e64 s[38:39], s10, v1
	v_cmp_lt_i32_e64 s[40:41], 4, v0
	v_cmp_gt_f32_e64 s[36:37], s10, v1
	s_and_b64 s[10:11], s[40:41], s[38:39]
	s_or_b64 s[10:11], s[36:37], s[10:11]
	v_cndmask_b32_e64 v4, 0, 1, s[10:11]
	v_readlane_b32 s10, v1, 5
	v_cmp_lt_i32_e64 s[40:41], 5, v0
	s_nop 0
	v_cmp_eq_f32_e64 s[38:39], s10, v1
	v_cmp_gt_f32_e64 s[36:37], s10, v1
	s_and_b64 s[10:11], s[40:41], s[38:39]
	s_or_b64 s[36:37], s[36:37], s[10:11]
	v_readlane_b32 s10, v1, 6
	v_addc_co_u32_e64 v2, s[36:37], v2, v4, s[36:37]
	s_nop 0
	v_cmp_eq_f32_e64 s[38:39], s10, v1
	v_cmp_lt_i32_e64 s[40:41], 6, v0
	v_cmp_gt_f32_e64 s[36:37], s10, v1
	s_and_b64 s[10:11], s[40:41], s[38:39]
	s_or_b64 s[10:11], s[36:37], s[10:11]
	v_cndmask_b32_e64 v4, 0, 1, s[10:11]
	v_readlane_b32 s10, v1, 7
	v_cmp_lt_i32_e64 s[40:41], 7, v0
	s_nop 0
	v_cmp_eq_f32_e64 s[38:39], s10, v1
	v_cmp_gt_f32_e64 s[36:37], s10, v1
	s_and_b64 s[10:11], s[40:41], s[38:39]
	s_or_b64 s[36:37], s[36:37], s[10:11]
	v_readlane_b32 s10, v1, 8
	v_addc_co_u32_e64 v2, s[36:37], v2, v4, s[36:37]
	s_nop 0
	v_cmp_eq_f32_e64 s[38:39], s10, v1
	v_cmp_lt_i32_e64 s[40:41], 8, v0
	v_cmp_gt_f32_e64 s[36:37], s10, v1
	s_and_b64 s[10:11], s[40:41], s[38:39]
	s_or_b64 s[10:11], s[36:37], s[10:11]
	v_cndmask_b32_e64 v4, 0, 1, s[10:11]
	v_readlane_b32 s10, v1, 9
	v_cmp_lt_i32_e64 s[40:41], 9, v0
	s_nop 0
	v_cmp_eq_f32_e64 s[38:39], s10, v1
	v_cmp_gt_f32_e64 s[36:37], s10, v1
	s_and_b64 s[10:11], s[40:41], s[38:39]
	s_or_b64 s[36:37], s[36:37], s[10:11]
	v_readlane_b32 s10, v1, 10
	v_addc_co_u32_e64 v2, s[36:37], v2, v4, s[36:37]
	s_nop 0
	v_cmp_eq_f32_e64 s[38:39], s10, v1
	v_cmp_lt_i32_e64 s[40:41], 10, v0
	v_cmp_gt_f32_e64 s[36:37], s10, v1
	s_and_b64 s[10:11], s[40:41], s[38:39]
	s_or_b64 s[10:11], s[36:37], s[10:11]
	v_cndmask_b32_e64 v4, 0, 1, s[10:11]
	v_readlane_b32 s10, v1, 11
	v_cmp_lt_i32_e64 s[40:41], 11, v0
	v_lshlrev_b32_e32 v0, 6, v0
	v_cmp_eq_f32_e64 s[38:39], s10, v1
	v_cmp_gt_f32_e64 s[36:37], s10, v1
	s_and_b64 s[10:11], s[40:41], s[38:39]
	s_or_b64 s[36:37], s[36:37], s[10:11]
	v_addc_co_u32_e64 v1, s[36:37], v2, v4, s[36:37]
	v_cmp_eq_u32_e64 s[36:37], s5, v1
	s_and_b64 s[10:11], vcc, s[36:37]
	v_cndmask_b32_e64 v1, 0, 1, s[10:11]
	v_cmp_ne_u32_e32 vcc, 0, v1
	s_ff1_i32_b64 s5, vcc
	s_cmp_lg_u64 vcc, 0
	s_cselect_b32 s11, s5, 0
	s_mul_i32 s5, s4, 12
	s_add_i32 s10, s11, s5
	s_ashr_i32 s5, s4, 31
	s_lshl_b64 s[16:17], s[4:5], 12
	s_or_b32 s16, s16, s2
	s_mul_i32 s5, s17, s61
	s_mul_hi_u32 s12, s16, s61
	s_add_i32 s19, s12, s5
	s_mul_i32 s18, s16, s61
	s_lshl_b64 s[18:19], s[18:19], 1
	s_add_u32 s5, s52, s18
	s_addc_u32 s12, s53, s19
	s_lshl_b32 s11, s11, 8
	s_add_u32 s18, s5, s11
	s_addc_u32 s19, s12, 0
	s_add_u32 s26, s18, 0xc00
	s_addc_u32 s27, s19, 0
	s_mul_hi_i32 s5, s4, 0x1800000
	s_mul_i32 s4, s4, 0x1800000
	s_add_u32 s4, s79, s4
	s_addc_u32 s5, s0, s5
	s_add_u32 s20, s4, s11
	s_addc_u32 s21, s5, 0
	s_add_u32 s22, s20, 0xc00
	s_addc_u32 s23, s21, 0
	s_lshl_b64 s[4:5], s[16:17], 12
	s_add_u32 s4, s68, s4
	s_addc_u32 s5, s69, s5
	s_add_u32 s24, s4, s11
	s_addc_u32 s25, s5, 0
	s_ashr_i32 s11, s10, 31
	s_lshl_b64 s[4:5], s[10:11], 14
	s_add_u32 s28, s1, s4
	s_addc_u32 s29, s60, s5
	s_lshl_b32 s4, s2, 2
	v_mov_b32_e32 v1, s4
	global_load_dword v2, v1, s[28:29]
	v_ashrrev_i32_e32 v1, 31, v0
	v_lshl_add_u64 v[0:1], v[0:1], 2, s[28:29]
	global_load_dword v0, v[0:1], off offset:252
	s_waitcnt vmcnt(0)
	v_sub_f32_e32 v0, v2, v0
	v_cmp_le_f32_e32 vcc, v0, v197
	s_ff1_i32_b64 s4, vcc
	s_cmp_lg_u64 vcc, 0
	s_cselect_b32 s48, s4, 0
	s_branch .LBB0_849

.LBB0_938:
	s_setprio 0
	s_nor_b64 s[4:5], s[96:97], s[6:7]
	s_add_i32 s0, s34, 1
	s_cmp_lt_i32 s0, s94
	s_cselect_b64 s[6:7], -1, 0
	s_and_b64 s[4:5], s[4:5], s[6:7]
	s_andn2_b64 vcc, exec, s[4:5]
	s_cbranch_vccnz .LBB0_990
	v_mov_b32_e32 v0, s82
	ds_read_b32 v0, v0
	v_readlane_b32 s4, v253, 20
	v_readlane_b32 s5, v253, 21
	s_and_b64 vcc, exec, s[4:5]
	s_waitcnt lgkmcnt(0)
	v_readfirstlane_b32 s8, v0
	v_mov_b32_e32 v0, s83
	ds_read_b32 v0, v0
	s_waitcnt vmcnt(0)
	s_waitcnt vmcnt(0) lgkmcnt(0)
	s_barrier
	v_readfirstlane_b32 s9, v0
	s_cbranch_vccnz .LBB0_989
	v_mbcnt_lo_u32_b32 v0, -1, 0
	v_mbcnt_hi_u32_b32 v0, -1, v0
	s_nop 0
	v_cmp_eq_u32_e32 vcc, 0, v0
	s_and_saveexec_b64 s[4:5], vcc
	s_cbranch_execz .LBB0_988
	v_readlane_b32 s1, v254, 21
	s_waitcnt vmcnt(0) expcnt(0) lgkmcnt(0)
	s_nop 0
	v_mov_b32_e32 v0, s1
	ds_read_b32 v2, v0
	v_readlane_b32 s1, v254, 22
	s_waitcnt lgkmcnt(0)
	v_cmp_ne_u32_e32 vcc, 0, v2
	v_mov_b32_e32 v0, s1
	ds_read_b32 v0, v0
	s_cbranch_vccnz .LBB0_956
	v_readlane_b32 s10, v253, 0
	v_readlane_b32 s11, v253, 1
	s_load_dwordx2 s[14:15], s[10:11], 0x4
	s_add_u32 s10, s8, 0x62b84200
	s_addc_u32 s11, s9, 0
	s_add_u32 s12, s8, 0x62b84400
	s_addc_u32 s13, s9, 0
	s_waitcnt lgkmcnt(0)
	s_mul_i32 s1, s14, s3
	s_add_u32 s14, s8, 0x62b84500
	s_mul_i32 s1, s1, s15
	s_addc_u32 s15, s9, 0
	s_add_u32 s16, s8, 0x62b84600
	s_addc_u32 s17, s9, 0
	s_add_u32 s18, s8, 0x62b84700
	s_addc_u32 s19, s9, 0
	s_add_u32 s20, s8, 0x62b84800
	s_addc_u32 s21, s9, 0
	s_add_u32 s22, s8, 0x62b84900
	s_addc_u32 s23, s9, 0
	s_add_u32 s24, s8, 0x62b84a00
	s_addc_u32 s25, s9, 0
	s_add_u32 s26, s8, 0x62b84b00
	s_addc_u32 s27, s9, 0
	s_add_u32 s28, s8, 0x62b84c00
	s_addc_u32 s29, s9, 0
	s_add_u32 s30, s8, 0x62b84d00
	s_addc_u32 s31, s9, 0
	s_add_u32 s36, s8, 0x62b84e00
	s_addc_u32 s37, s9, 0
	s_add_u32 s38, s8, 0x62b84f00
	s_addc_u32 s39, s9, 0
	s_add_u32 s40, s8, 0x62b85000
	s_addc_u32 s41, s9, 0
	s_add_u32 s42, s8, 0x62b85100
	s_addc_u32 s43, s9, 0
	s_add_u32 s44, s8, 0x62b85200
	s_addc_u32 s45, s9, 0
	s_add_u32 s46, s8, 0x62b85300
	s_addc_u32 s47, s9, 0
	s_mov_b32 s2, 1
	s_branch .LBB0_944
